# attention unit epilogue: sub-norm gain quads loaded once (8 in flight) instead of load+vmcnt(0) before each of 16 output stores
# speedup vs baseline: 1.0106x; 1.0106x over previous
.LBB0_1109:
	s_cmp_gt_u32 s57, 3
	s_waitcnt lgkmcnt(0)
	s_barrier
	s_cbranch_scc1 .LBB0_1094
	s_lshl_b64 s[4:5], s[6:7], 2
	s_add_u32 s20, s20, s4
	s_addc_u32 s21, s21, s5
	v_add_f32_e32 v1, v1, v66
	v_add_f32_e32 v66, v67, v68
	s_add_u32 s16, s16, 0x16100000
	v_or_b32_e32 v67, s54, v149
	v_mul_f32_e32 v1, 0x3fb8aa3b, v1
	v_mul_f32_e32 v66, 0x3fb8aa3b, v66
	s_addc_u32 s17, s17, 0
	s_add_i32 s4, 0, 0x12000
	v_mul_lo_u32 v67, v67, s65
	v_exp_f32_e32 v1, v1
	v_exp_f32_e32 v66, v66
	v_add3_u32 v78, s4, v130, v67
	ds_read_b128 v[70:73], v78
	s_brev_b32 s4, 60
	v_sub_f32_e32 v1, v1, v66
	v_add_f32_e32 v68, v146, v1
	v_or_b32_e32 v66, s56, v149
	s_waitcnt lgkmcnt(0)
	v_pk_fma_f32 v[64:65], v[68:69], v[72:73], v[64:65] op_sel_hi:[0,1,1] neg_lo:[1,0,0] neg_hi:[1,0,0]
	v_pk_fma_f32 v[62:63], v[68:69], v[70:71], v[62:63] op_sel_hi:[0,1,1] neg_lo:[1,0,0] neg_hi:[1,0,0]
	ds_read_b128 v[70:73], v78 offset:64
	v_mov_b32_e32 v74, v65
	v_lshlrev_b32_e32 v1, 4, v148
	s_waitcnt lgkmcnt(0)
	v_pk_fma_f32 v[58:59], v[68:69], v[70:71], v[58:59] op_sel_hi:[0,1,1] neg_lo:[1,0,0] neg_hi:[1,0,0]
	v_pk_fma_f32 v[60:61], v[68:69], v[72:73], v[60:61] op_sel_hi:[0,1,1] neg_lo:[1,0,0] neg_hi:[1,0,0]
	v_mov_b32_e32 v72, v63
	v_mov_b32_e32 v73, v59
	v_mov_b32_e32 v70, v62
	v_mov_b32_e32 v71, v58
	v_pk_mul_f32 v[72:73], v[72:73], v[72:73]
	v_mov_b32_e32 v75, v61
	v_pk_fma_f32 v[70:71], v[70:71], v[70:71], v[72:73]
	v_mov_b32_e32 v72, v64
	v_mov_b32_e32 v73, v60
	v_pk_mul_f32 v[74:75], v[74:75], v[74:75]
	s_nop 0
	v_pk_fma_f32 v[72:73], v[72:73], v[72:73], v[74:75]
	s_nop 0
	v_pk_add_f32 v[74:75], v[70:71], v[72:73]
	ds_read_b128 v[70:73], v78 offset:128
	s_waitcnt lgkmcnt(0)
	v_pk_fma_f32 v[54:55], v[68:69], v[70:71], v[54:55] op_sel_hi:[0,1,1] neg_lo:[1,0,0] neg_hi:[1,0,0]
	v_pk_fma_f32 v[56:57], v[68:69], v[72:73], v[56:57] op_sel_hi:[0,1,1] neg_lo:[1,0,0] neg_hi:[1,0,0]
	v_pk_mul_f32 v[70:71], v[56:57], v[56:57]
	v_pk_mul_f32 v[72:73], v[54:55], v[54:55]
	s_nop 0
	v_pk_mov_b32 v[76:77], v[72:73], v[70:71] op_sel:[1,0]
	v_mov_b32_e32 v73, v71
	v_pk_add_f32 v[76:77], v[76:77], v[72:73]
	ds_read_b128 v[70:73], v78 offset:192
	s_waitcnt lgkmcnt(0)
	v_pk_fma_f32 v[52:53], v[68:69], v[72:73], v[52:53] op_sel_hi:[0,1,1] neg_lo:[1,0,0] neg_hi:[1,0,0]
	v_pk_fma_f32 v[50:51], v[68:69], v[70:71], v[50:51] op_sel_hi:[0,1,1] neg_lo:[1,0,0] neg_hi:[1,0,0]
	ds_read_b128 v[70:73], v78 offset:256
	s_waitcnt lgkmcnt(0)
	v_pk_fma_f32 v[46:47], v[68:69], v[70:71], v[46:47] op_sel_hi:[0,1,1] neg_lo:[1,0,0] neg_hi:[1,0,0]
	v_pk_fma_f32 v[48:49], v[68:69], v[72:73], v[48:49] op_sel_hi:[0,1,1] neg_lo:[1,0,0] neg_hi:[1,0,0]
	v_mul_f32_e32 v67, v46, v46
	v_mul_f32_e32 v69, v47, v47
	v_pk_add_f32 v[70:71], v[74:75], v[74:75] op_sel:[0,1] op_sel_hi:[1,0]
	v_pk_add_f32 v[72:73], v[76:77], v[76:77] op_sel:[0,1] op_sel_hi:[1,0]
	v_mov_b32_e32 v71, v67
	v_mov_b32_e32 v73, v69
	v_pk_add_f32 v[70:71], v[70:71], v[72:73]
	v_mul_f32_e32 v72, v51, v51
	v_mul_f32_e32 v74, v53, v53
	v_mul_f32_e32 v79, v48, v48
	v_mul_f32_e32 v80, v49, v49
	v_pk_fma_f32 v[72:73], v[50:51], v[50:51], v[72:73] op_sel_hi:[1,1,0]
	v_pk_fma_f32 v[74:75], v[52:53], v[52:53], v[74:75] op_sel_hi:[1,1,0]
	v_mov_b32_e32 v73, v79
	v_mov_b32_e32 v75, v80
	v_pk_add_f32 v[72:73], v[72:73], v[74:75]
	s_nop 0
	v_pk_add_f32 v[76:77], v[70:71], v[72:73]
	ds_read_b128 v[70:73], v78 offset:320
	s_waitcnt lgkmcnt(0)
	v_pk_fma_f32 v[42:43], v[68:69], v[70:71], v[42:43] op_sel_hi:[0,1,1] neg_lo:[1,0,0] neg_hi:[1,0,0]
	v_pk_fma_f32 v[44:45], v[68:69], v[72:73], v[44:45] op_sel_hi:[0,1,1] neg_lo:[1,0,0] neg_hi:[1,0,0]
	v_pk_mul_f32 v[70:71], v[44:45], v[44:45]
	v_pk_mul_f32 v[72:73], v[42:43], v[42:43]
	s_nop 0
	v_pk_mov_b32 v[74:75], v[72:73], v[70:71] op_sel:[1,0]
	v_mov_b32_e32 v73, v71
	v_pk_add_f32 v[80:81], v[74:75], v[72:73]
	ds_read_b128 v[70:73], v78 offset:384
	s_waitcnt lgkmcnt(0)
	v_pk_fma_f32 v[40:41], v[68:69], v[72:73], v[40:41] op_sel_hi:[0,1,1] neg_lo:[1,0,0] neg_hi:[1,0,0]
	ds_read_b128 v[72:75], v78 offset:448
	v_pk_fma_f32 v[38:39], v[68:69], v[70:71], v[38:39] op_sel_hi:[0,1,1] neg_lo:[1,0,0] neg_hi:[1,0,0]
	s_waitcnt lgkmcnt(0)
	v_pk_fma_f32 v[72:73], v[68:69], v[72:73], v[34:35] op_sel_hi:[0,1,1] neg_lo:[1,0,0] neg_hi:[1,0,0]
	v_pk_fma_f32 v[70:71], v[68:69], v[74:75], v[36:37] op_sel_hi:[0,1,1] neg_lo:[1,0,0] neg_hi:[1,0,0]
	v_mul_f32_e32 v36, v72, v72
	v_pk_add_f32 v[34:35], v[76:77], v[76:77] op_sel:[0,1] op_sel_hi:[1,0]
	v_mul_f32_e32 v67, v73, v73
	v_mov_b32_e32 v35, v36
	v_pk_add_f32 v[36:37], v[80:81], v[80:81] op_sel:[0,1] op_sel_hi:[1,0]
	v_mul_f32_e32 v74, v41, v41
	v_mov_b32_e32 v37, v67
	v_pk_add_f32 v[34:35], v[34:35], v[36:37]
	v_mul_f32_e32 v36, v39, v39
	v_mul_f32_e32 v69, v70, v70
	v_mul_f32_e32 v79, v71, v71
	v_pk_fma_f32 v[36:37], v[38:39], v[38:39], v[36:37] op_sel_hi:[1,1,0]
	v_pk_fma_f32 v[74:75], v[40:41], v[40:41], v[74:75] op_sel_hi:[1,1,0]
	v_mov_b32_e32 v37, v69
	v_mov_b32_e32 v75, v79
	v_pk_add_f32 v[36:37], v[36:37], v[74:75]
	v_ashrrev_i32_e32 v67, 31, v66
	v_pk_add_f32 v[34:35], v[34:35], v[36:37]
	ds_read_b128 v[80:83], v78 offset:8448
	v_pk_add_f32 v[34:35], v[34:35], v[34:35] op_sel:[0,1] op_sel_hi:[1,0]
	v_lshlrev_b32_e32 v74, 3, v148
	v_mov_b32_e32 v35, v34
	s_nop 1
	v_permlane16_swap_b32_e32 v34, v35
	v_add_f32_e32 v69, v34, v35
	v_lshlrev_b64 v[34:35], 12, v[66:67]
	v_lshl_add_u64 v[34:35], s[16:17], 0, v[34:35]
	v_mov_b32_e32 v79, v69
	v_lshl_add_u64 v[34:35], v[34:35], 0, s[62:63]
	v_mov_b32_e32 v75, v0
	v_permlane32_swap_b32_e32 v69, v79
	v_lshl_add_u64 v[76:77], v[34:35], 0, v[74:75]
	global_load_dwordx4 v[208:211], v1, s[20:21]
	global_load_dwordx4 v[212:215], v1, s[20:21] offset:64
	global_load_dwordx4 v[216:219], v1, s[20:21] offset:128
	global_load_dwordx4 v[220:223], v1, s[20:21] offset:192
	global_load_dwordx4 v[224:227], v1, s[20:21] offset:256
	global_load_dwordx4 v[228:231], v1, s[20:21] offset:320
	global_load_dwordx4 v[244:247], v1, s[20:21] offset:384
	global_load_dwordx4 v[248:251], v1, s[20:21] offset:448
	s_waitcnt lgkmcnt(0)
	v_pk_fma_f32 v[32:33], v[68:69], v[82:83], v[32:33] op_sel_hi:[0,1,1] neg_lo:[1,0,0] neg_hi:[1,0,0]
	v_pk_fma_f32 v[30:31], v[68:69], v[80:81], v[30:31] op_sel_hi:[0,1,1] neg_lo:[1,0,0] neg_hi:[1,0,0]
	ds_read_b128 v[80:83], v78 offset:8512
	v_mov_b32_e32 v84, v33
	s_waitcnt lgkmcnt(0)
	v_pk_fma_f32 v[26:27], v[68:69], v[80:81], v[26:27] op_sel_hi:[0,1,1] neg_lo:[1,0,0] neg_hi:[1,0,0]
	v_pk_fma_f32 v[28:29], v[68:69], v[82:83], v[28:29] op_sel_hi:[0,1,1] neg_lo:[1,0,0] neg_hi:[1,0,0]
	v_mov_b32_e32 v82, v31
	v_mov_b32_e32 v83, v27
	v_mov_b32_e32 v80, v30
	v_mov_b32_e32 v81, v26
	v_pk_mul_f32 v[82:83], v[82:83], v[82:83]
	v_mov_b32_e32 v85, v29
	v_pk_fma_f32 v[80:81], v[80:81], v[80:81], v[82:83]
	v_mov_b32_e32 v82, v32
	v_mov_b32_e32 v83, v28
	v_pk_mul_f32 v[84:85], v[84:85], v[84:85]
	s_nop 0
	v_pk_fma_f32 v[82:83], v[82:83], v[82:83], v[84:85]
	s_nop 0
	v_pk_add_f32 v[84:85], v[80:81], v[82:83]
	ds_read_b128 v[80:83], v78 offset:8576
	s_waitcnt lgkmcnt(0)
	v_pk_fma_f32 v[22:23], v[68:69], v[80:81], v[22:23] op_sel_hi:[0,1,1] neg_lo:[1,0,0] neg_hi:[1,0,0]
	v_pk_fma_f32 v[24:25], v[68:69], v[82:83], v[24:25] op_sel_hi:[0,1,1] neg_lo:[1,0,0] neg_hi:[1,0,0]
	v_pk_mul_f32 v[80:81], v[24:25], v[24:25]
	v_pk_mul_f32 v[82:83], v[22:23], v[22:23]
	s_nop 0
	v_pk_mov_b32 v[86:87], v[82:83], v[80:81] op_sel:[1,0]
	v_mov_b32_e32 v83, v81
	v_pk_add_f32 v[86:87], v[86:87], v[82:83]
	ds_read_b128 v[80:83], v78 offset:8640
	s_waitcnt lgkmcnt(0)
	v_pk_fma_f32 v[20:21], v[68:69], v[82:83], v[20:21] op_sel_hi:[0,1,1] neg_lo:[1,0,0] neg_hi:[1,0,0]
	v_pk_fma_f32 v[18:19], v[68:69], v[80:81], v[18:19] op_sel_hi:[0,1,1] neg_lo:[1,0,0] neg_hi:[1,0,0]
	ds_read_b128 v[80:83], v78 offset:8704
	s_waitcnt lgkmcnt(0)
	v_pk_fma_f32 v[14:15], v[68:69], v[80:81], v[14:15] op_sel_hi:[0,1,1] neg_lo:[1,0,0] neg_hi:[1,0,0]
	v_pk_fma_f32 v[16:17], v[68:69], v[82:83], v[16:17] op_sel_hi:[0,1,1] neg_lo:[1,0,0] neg_hi:[1,0,0]
	v_mul_f32_e32 v67, v14, v14
	v_mul_f32_e32 v88, v15, v15
	v_pk_add_f32 v[80:81], v[84:85], v[84:85] op_sel:[0,1] op_sel_hi:[1,0]
	v_pk_add_f32 v[82:83], v[86:87], v[86:87] op_sel:[0,1] op_sel_hi:[1,0]
	v_mov_b32_e32 v81, v67
	v_mov_b32_e32 v83, v88
	v_pk_add_f32 v[80:81], v[80:81], v[82:83]
	v_mul_f32_e32 v82, v19, v19
	v_mul_f32_e32 v84, v21, v21
	v_mul_f32_e32 v89, v16, v16
	v_mul_f32_e32 v90, v17, v17
	v_pk_fma_f32 v[82:83], v[18:19], v[18:19], v[82:83] op_sel_hi:[1,1,0]
	v_pk_fma_f32 v[84:85], v[20:21], v[20:21], v[84:85] op_sel_hi:[1,1,0]
	v_mov_b32_e32 v83, v89
	v_mov_b32_e32 v85, v90
	v_pk_add_f32 v[82:83], v[82:83], v[84:85]
	s_nop 0
	v_pk_add_f32 v[84:85], v[80:81], v[82:83]
	ds_read_b128 v[80:83], v78 offset:8768
	s_waitcnt lgkmcnt(0)
	v_pk_fma_f32 v[10:11], v[68:69], v[80:81], v[10:11] op_sel_hi:[0,1,1] neg_lo:[1,0,0] neg_hi:[1,0,0]
	v_pk_fma_f32 v[12:13], v[68:69], v[82:83], v[12:13] op_sel_hi:[0,1,1] neg_lo:[1,0,0] neg_hi:[1,0,0]
	v_pk_mul_f32 v[80:81], v[12:13], v[12:13]
	v_pk_mul_f32 v[82:83], v[10:11], v[10:11]
	s_nop 0
	v_pk_mov_b32 v[86:87], v[82:83], v[80:81] op_sel:[1,0]
	v_mov_b32_e32 v83, v81
	v_pk_add_f32 v[86:87], v[86:87], v[82:83]
	ds_read_b128 v[80:83], v78 offset:8832
	s_waitcnt lgkmcnt(0)
	v_pk_fma_f32 v[8:9], v[68:69], v[82:83], v[8:9] op_sel_hi:[0,1,1] neg_lo:[1,0,0] neg_hi:[1,0,0]
	v_pk_fma_f32 v[6:7], v[68:69], v[80:81], v[6:7] op_sel_hi:[0,1,1] neg_lo:[1,0,0] neg_hi:[1,0,0]
	ds_read_b128 v[80:83], v78 offset:8896
	s_waitcnt lgkmcnt(0)
	v_pk_fma_f32 v[2:3], v[68:69], v[80:81], v[2:3] op_sel_hi:[0,1,1] neg_lo:[1,0,0] neg_hi:[1,0,0]
	v_pk_fma_f32 v[4:5], v[68:69], v[82:83], v[4:5] op_sel_hi:[0,1,1] neg_lo:[1,0,0] neg_hi:[1,0,0]
	v_mul_f32_e32 v67, v2, v2
	v_mul_f32_e32 v68, v3, v3
	v_pk_add_f32 v[80:81], v[84:85], v[84:85] op_sel:[0,1] op_sel_hi:[1,0]
	v_pk_add_f32 v[82:83], v[86:87], v[86:87] op_sel:[0,1] op_sel_hi:[1,0]
	v_mov_b32_e32 v81, v67
	v_mov_b32_e32 v83, v68
	v_mul_f32_e32 v68, v7, v7
	v_pk_add_f32 v[80:81], v[80:81], v[82:83]
	v_pk_fma_f32 v[82:83], v[6:7], v[6:7], v[68:69] op_sel_hi:[1,1,0]
	v_mul_f32_e32 v68, v9, v9
	v_mul_f32_e32 v78, v4, v4
	v_mul_f32_e32 v88, v5, v5
	v_pk_fma_f32 v[84:85], v[8:9], v[8:9], v[68:69] op_sel_hi:[1,1,0]
	v_mov_b32_e32 v83, v78
	v_mov_b32_e32 v85, v88
	v_pk_add_f32 v[82:83], v[82:83], v[84:85]
	s_nop 0
	v_pk_add_f32 v[80:81], v[80:81], v[82:83]
	s_nop 0
	v_pk_add_f32 v[80:81], v[80:81], v[80:81] op_sel:[0,1] op_sel_hi:[1,0]
	s_nop 0
	v_mov_b32_e32 v67, v80
	s_nop 1
	v_permlane16_swap_b32_e32 v80, v67
	v_add_f32_e32 v68, v80, v67
	v_mov_b32_e32 v78, v68
	s_nop 1
	v_permlane32_swap_b32_e32 v68, v78
	v_pk_add_f32 v[68:69], v[68:69], v[78:79]
	s_nop 0
	v_pk_fma_f32 v[68:69], v[68:69], s[4:5], v[178:179] op_sel_hi:[1,0,0]
	s_nop 0
	v_mul_f32_e32 v67, 0x4b800000, v69
	v_cmp_gt_f32_e64 s[4:5], s84, v69
	v_cmp_gt_f32_e32 vcc, s84, v68
	s_nop 0
	v_cndmask_b32_e64 v67, v69, v67, s[4:5]
	v_rsq_f32_e32 v67, v67
	s_nop 0
	v_mul_f32_e32 v69, 0x45800000, v67
	v_cndmask_b32_e64 v67, v67, v69, s[4:5]
	v_mul_f32_e32 v78, v147, v67
	v_pk_mul_f32 v[62:63], v[62:63], v[78:79] op_sel_hi:[1,0]
	v_pk_mul_f32 v[64:65], v[64:65], v[78:79] op_sel_hi:[1,0]
	s_waitcnt vmcnt(0)
	v_pk_mul_f32 v[34:35], v[208:209], v[62:63]
	v_pk_mul_f32 v[36:37], v[210:211], v[64:65]
	v_cvt_pk_bf16_f32 v34, v34, v35
	v_cvt_pk_bf16_f32 v35, v36, v37
	global_store_dwordx2 v[76:77], v[34:35], off offset:2048
	v_pk_mul_f32 v[58:59], v[58:59], v[78:79] op_sel_hi:[1,0]
	v_pk_mul_f32 v[60:61], v[60:61], v[78:79] op_sel_hi:[1,0]
	v_pk_mul_f32 v[54:55], v[54:55], v[78:79] op_sel_hi:[1,0]
	v_pk_mul_f32 v[56:57], v[56:57], v[78:79] op_sel_hi:[1,0]
	v_pk_mul_f32 v[50:51], v[50:51], v[78:79] op_sel_hi:[1,0]
	v_pk_mul_f32 v[52:53], v[52:53], v[78:79] op_sel_hi:[1,0]
	v_pk_mul_f32 v[46:47], v[46:47], v[78:79] op_sel_hi:[1,0]
	v_pk_mul_f32 v[48:49], v[48:49], v[78:79] op_sel_hi:[1,0]
	v_pk_mul_f32 v[42:43], v[42:43], v[78:79] op_sel_hi:[1,0]
	v_pk_mul_f32 v[44:45], v[44:45], v[78:79] op_sel_hi:[1,0]
	v_pk_mul_f32 v[38:39], v[38:39], v[78:79] op_sel_hi:[1,0]
	v_pk_mul_f32 v[40:41], v[40:41], v[78:79] op_sel_hi:[1,0]
	v_pk_mul_f32 v[36:37], v[214:215], v[60:61]
	v_pk_mul_f32 v[34:35], v[212:213], v[58:59]
	s_nop 0
	v_cvt_pk_bf16_f32 v34, v34, v35
	v_cvt_pk_bf16_f32 v35, v36, v37
	global_store_dwordx2 v[76:77], v[34:35], off offset:2080
	v_pk_mul_f32 v[36:37], v[218:219], v[56:57]
	v_pk_mul_f32 v[34:35], v[216:217], v[54:55]
	s_nop 0
	v_cvt_pk_bf16_f32 v34, v34, v35
	v_cvt_pk_bf16_f32 v35, v36, v37
	global_store_dwordx2 v[76:77], v[34:35], off offset:2112
	v_pk_mul_f32 v[36:37], v[222:223], v[52:53]
	v_pk_mul_f32 v[34:35], v[220:221], v[50:51]
	s_nop 0
	v_cvt_pk_bf16_f32 v34, v34, v35
	v_cvt_pk_bf16_f32 v35, v36, v37
	global_store_dwordx2 v[76:77], v[34:35], off offset:2144
	v_pk_mul_f32 v[36:37], v[226:227], v[48:49]
	v_pk_mul_f32 v[34:35], v[224:225], v[46:47]
	s_nop 0
	v_cvt_pk_bf16_f32 v34, v34, v35
	v_cvt_pk_bf16_f32 v35, v36, v37
	global_store_dwordx2 v[76:77], v[34:35], off offset:2176
	v_pk_mul_f32 v[36:37], v[230:231], v[44:45]
	v_pk_mul_f32 v[34:35], v[228:229], v[42:43]
	s_nop 0
	v_cvt_pk_bf16_f32 v34, v34, v35
	v_cvt_pk_bf16_f32 v35, v36, v37
	global_store_dwordx2 v[76:77], v[34:35], off offset:2208
	v_pk_mul_f32 v[36:37], v[246:247], v[40:41]
	v_pk_mul_f32 v[34:35], v[244:245], v[38:39]
	v_pk_mul_f32 v[38:39], v[72:73], v[78:79] op_sel_hi:[1,0]
	v_cvt_pk_bf16_f32 v34, v34, v35
	v_cvt_pk_bf16_f32 v35, v36, v37
	global_store_dwordx2 v[76:77], v[34:35], off offset:2240
	v_pk_mul_f32 v[40:41], v[70:71], v[78:79] op_sel_hi:[1,0]
	v_pk_mul_f32 v[34:35], v[38:39], v[248:249]
	v_pk_mul_f32 v[36:37], v[40:41], v[250:251]
	v_cvt_pk_bf16_f32 v34, v34, v35
	v_cvt_pk_bf16_f32 v35, v36, v37
	global_store_dwordx2 v[76:77], v[34:35], off offset:2272
	v_mul_f32_e32 v34, 0x4b800000, v68
	v_cndmask_b32_e32 v34, v68, v34, vcc
	v_rsq_f32_e32 v34, v34
	s_nop 0
	v_mul_f32_e32 v35, 0x45800000, v34
	v_cndmask_b32_e32 v34, v34, v35, vcc
	v_mul_f32_e32 v38, v147, v34
	v_or_b32_e32 v34, 16, v66
	v_ashrrev_i32_e32 v35, 31, v34
	v_lshlrev_b64 v[34:35], 12, v[34:35]
	v_lshl_add_u64 v[34:35], s[16:17], 0, v[34:35]
	v_lshl_add_u64 v[34:35], v[34:35], 0, s[62:63]
	v_lshl_add_u64 v[40:41], v[34:35], 0, v[74:75]
	v_pk_mul_f32 v[30:31], v[30:31], v[38:39] op_sel_hi:[1,0]
	v_pk_mul_f32 v[32:33], v[32:33], v[38:39] op_sel_hi:[1,0]
	v_pk_mul_f32 v[26:27], v[26:27], v[38:39] op_sel_hi:[1,0]
	v_pk_mul_f32 v[28:29], v[28:29], v[38:39] op_sel_hi:[1,0]
	v_pk_mul_f32 v[22:23], v[22:23], v[38:39] op_sel_hi:[1,0]
	v_pk_mul_f32 v[24:25], v[24:25], v[38:39] op_sel_hi:[1,0]
	v_pk_mul_f32 v[18:19], v[18:19], v[38:39] op_sel_hi:[1,0]
	v_pk_mul_f32 v[20:21], v[20:21], v[38:39] op_sel_hi:[1,0]
	v_pk_mul_f32 v[14:15], v[14:15], v[38:39] op_sel_hi:[1,0]
	v_pk_mul_f32 v[16:17], v[16:17], v[38:39] op_sel_hi:[1,0]
	v_pk_mul_f32 v[10:11], v[10:11], v[38:39] op_sel_hi:[1,0]
	v_pk_mul_f32 v[12:13], v[12:13], v[38:39] op_sel_hi:[1,0]
	v_pk_mul_f32 v[6:7], v[6:7], v[38:39] op_sel_hi:[1,0]
	v_pk_mul_f32 v[8:9], v[8:9], v[38:39] op_sel_hi:[1,0]
	v_pk_mul_f32 v[2:3], v[2:3], v[38:39] op_sel_hi:[1,0]
	v_pk_mul_f32 v[4:5], v[4:5], v[38:39] op_sel_hi:[1,0]
	v_pk_mul_f32 v[32:33], v[210:211], v[32:33]
	v_pk_mul_f32 v[30:31], v[208:209], v[30:31]
	s_nop 0
	v_cvt_pk_bf16_f32 v30, v30, v31
	v_cvt_pk_bf16_f32 v31, v32, v33
	global_store_dwordx2 v[40:41], v[30:31], off offset:2048
	v_pk_mul_f32 v[28:29], v[214:215], v[28:29]
	v_pk_mul_f32 v[26:27], v[212:213], v[26:27]
	s_nop 0
	v_cvt_pk_bf16_f32 v26, v26, v27
	v_cvt_pk_bf16_f32 v27, v28, v29
	global_store_dwordx2 v[40:41], v[26:27], off offset:2080
	v_pk_mul_f32 v[24:25], v[218:219], v[24:25]
	v_pk_mul_f32 v[22:23], v[216:217], v[22:23]
	s_nop 0
	v_cvt_pk_bf16_f32 v22, v22, v23
	v_cvt_pk_bf16_f32 v23, v24, v25
	global_store_dwordx2 v[40:41], v[22:23], off offset:2112
	v_pk_mul_f32 v[20:21], v[222:223], v[20:21]
	v_pk_mul_f32 v[18:19], v[220:221], v[18:19]
	s_nop 0
	v_cvt_pk_bf16_f32 v18, v18, v19
	v_cvt_pk_bf16_f32 v19, v20, v21
	global_store_dwordx2 v[40:41], v[18:19], off offset:2144
	v_pk_mul_f32 v[16:17], v[226:227], v[16:17]
	v_pk_mul_f32 v[14:15], v[224:225], v[14:15]
	s_nop 0
	v_cvt_pk_bf16_f32 v14, v14, v15
	v_cvt_pk_bf16_f32 v15, v16, v17
	global_store_dwordx2 v[40:41], v[14:15], off offset:2176
	v_pk_mul_f32 v[12:13], v[230:231], v[12:13]
	v_pk_mul_f32 v[10:11], v[228:229], v[10:11]
	s_nop 0
	v_cvt_pk_bf16_f32 v10, v10, v11
	v_cvt_pk_bf16_f32 v11, v12, v13
	global_store_dwordx2 v[40:41], v[10:11], off offset:2208
	v_pk_mul_f32 v[8:9], v[246:247], v[8:9]
	v_pk_mul_f32 v[6:7], v[244:245], v[6:7]
	s_nop 0
	v_cvt_pk_bf16_f32 v6, v6, v7
	v_cvt_pk_bf16_f32 v7, v8, v9
	global_store_dwordx2 v[40:41], v[6:7], off offset:2240
	v_pk_mul_f32 v[4:5], v[4:5], v[250:251]
	v_pk_mul_f32 v[2:3], v[2:3], v[248:249]
	s_nop 0
	v_cvt_pk_bf16_f32 v2, v2, v3
	v_cvt_pk_bf16_f32 v3, v4, v5
	global_store_dwordx2 v[40:41], v[2:3], off offset:2272
	s_branch .LBB0_1094

.LBB0_1122:
	s_cmp_gt_u32 s35, 3
	s_waitcnt lgkmcnt(0)
	s_barrier
	s_cbranch_scc1 .LBB0_1112
	s_lshl_b64 s[4:5], s[6:7], 2
	s_add_u32 s14, s14, s4
	s_addc_u32 s15, s15, s5
	v_add_f32_e32 v1, v1, v66
	v_add_f32_e32 v66, v67, v68
	s_add_u32 s12, s12, 0x16100000
	v_or_b32_e32 v67, s29, v145
	v_mul_f32_e32 v1, 0x3fb8aa3b, v1
	v_mul_f32_e32 v66, 0x3fb8aa3b, v66
	s_addc_u32 s13, s13, 0
	s_add_i32 s4, 0, 0x12000
	v_mul_lo_u32 v67, v67, s65
	v_exp_f32_e32 v1, v1
	v_exp_f32_e32 v66, v66
	v_add3_u32 v78, s4, v132, v67
	ds_read_b128 v[70:73], v78
	s_brev_b32 s4, 60
	v_sub_f32_e32 v1, v1, v66
	v_add_f32_e32 v68, v146, v1
	v_or_b32_e32 v66, s34, v145
	s_waitcnt lgkmcnt(0)
	v_pk_fma_f32 v[64:65], v[68:69], v[72:73], v[64:65] op_sel_hi:[0,1,1] neg_lo:[1,0,0] neg_hi:[1,0,0]
	v_pk_fma_f32 v[62:63], v[68:69], v[70:71], v[62:63] op_sel_hi:[0,1,1] neg_lo:[1,0,0] neg_hi:[1,0,0]
	ds_read_b128 v[70:73], v78 offset:64
	v_mov_b32_e32 v74, v65
	v_lshlrev_b32_e32 v1, 4, v144
	s_waitcnt lgkmcnt(0)
	v_pk_fma_f32 v[58:59], v[68:69], v[70:71], v[58:59] op_sel_hi:[0,1,1] neg_lo:[1,0,0] neg_hi:[1,0,0]
	v_pk_fma_f32 v[60:61], v[68:69], v[72:73], v[60:61] op_sel_hi:[0,1,1] neg_lo:[1,0,0] neg_hi:[1,0,0]
	v_mov_b32_e32 v72, v63
	v_mov_b32_e32 v73, v59
	v_mov_b32_e32 v70, v62
	v_mov_b32_e32 v71, v58
	v_pk_mul_f32 v[72:73], v[72:73], v[72:73]
	v_mov_b32_e32 v75, v61
	v_pk_fma_f32 v[70:71], v[70:71], v[70:71], v[72:73]
	v_mov_b32_e32 v72, v64
	v_mov_b32_e32 v73, v60
	v_pk_mul_f32 v[74:75], v[74:75], v[74:75]
	s_nop 0
	v_pk_fma_f32 v[72:73], v[72:73], v[72:73], v[74:75]
	s_nop 0
	v_pk_add_f32 v[74:75], v[70:71], v[72:73]
	ds_read_b128 v[70:73], v78 offset:128
	s_waitcnt lgkmcnt(0)
	v_pk_fma_f32 v[54:55], v[68:69], v[70:71], v[54:55] op_sel_hi:[0,1,1] neg_lo:[1,0,0] neg_hi:[1,0,0]
	v_pk_fma_f32 v[56:57], v[68:69], v[72:73], v[56:57] op_sel_hi:[0,1,1] neg_lo:[1,0,0] neg_hi:[1,0,0]
	v_pk_mul_f32 v[70:71], v[56:57], v[56:57]
	v_pk_mul_f32 v[72:73], v[54:55], v[54:55]
	s_nop 0
	v_pk_mov_b32 v[76:77], v[72:73], v[70:71] op_sel:[1,0]
	v_mov_b32_e32 v73, v71
	v_pk_add_f32 v[76:77], v[76:77], v[72:73]
	ds_read_b128 v[70:73], v78 offset:192
	s_waitcnt lgkmcnt(0)
	v_pk_fma_f32 v[52:53], v[68:69], v[72:73], v[52:53] op_sel_hi:[0,1,1] neg_lo:[1,0,0] neg_hi:[1,0,0]
	v_pk_fma_f32 v[50:51], v[68:69], v[70:71], v[50:51] op_sel_hi:[0,1,1] neg_lo:[1,0,0] neg_hi:[1,0,0]
	ds_read_b128 v[70:73], v78 offset:256
	s_waitcnt lgkmcnt(0)
	v_pk_fma_f32 v[46:47], v[68:69], v[70:71], v[46:47] op_sel_hi:[0,1,1] neg_lo:[1,0,0] neg_hi:[1,0,0]
	v_pk_fma_f32 v[48:49], v[68:69], v[72:73], v[48:49] op_sel_hi:[0,1,1] neg_lo:[1,0,0] neg_hi:[1,0,0]
	v_mul_f32_e32 v67, v46, v46
	v_mul_f32_e32 v69, v47, v47
	v_pk_add_f32 v[70:71], v[74:75], v[74:75] op_sel:[0,1] op_sel_hi:[1,0]
	v_pk_add_f32 v[72:73], v[76:77], v[76:77] op_sel:[0,1] op_sel_hi:[1,0]
	v_mov_b32_e32 v71, v67
	v_mov_b32_e32 v73, v69
	v_pk_add_f32 v[70:71], v[70:71], v[72:73]
	v_mul_f32_e32 v72, v51, v51
	v_mul_f32_e32 v74, v53, v53
	v_mul_f32_e32 v79, v48, v48
	v_mul_f32_e32 v80, v49, v49
	v_pk_fma_f32 v[72:73], v[50:51], v[50:51], v[72:73] op_sel_hi:[1,1,0]
	v_pk_fma_f32 v[74:75], v[52:53], v[52:53], v[74:75] op_sel_hi:[1,1,0]
	v_mov_b32_e32 v73, v79
	v_mov_b32_e32 v75, v80
	v_pk_add_f32 v[72:73], v[72:73], v[74:75]
	s_nop 0
	v_pk_add_f32 v[76:77], v[70:71], v[72:73]
	ds_read_b128 v[70:73], v78 offset:320
	s_waitcnt lgkmcnt(0)
	v_pk_fma_f32 v[42:43], v[68:69], v[70:71], v[42:43] op_sel_hi:[0,1,1] neg_lo:[1,0,0] neg_hi:[1,0,0]
	v_pk_fma_f32 v[44:45], v[68:69], v[72:73], v[44:45] op_sel_hi:[0,1,1] neg_lo:[1,0,0] neg_hi:[1,0,0]
	v_pk_mul_f32 v[70:71], v[44:45], v[44:45]
	v_pk_mul_f32 v[72:73], v[42:43], v[42:43]
	s_nop 0
	v_pk_mov_b32 v[74:75], v[72:73], v[70:71] op_sel:[1,0]
	v_mov_b32_e32 v73, v71
	v_pk_add_f32 v[80:81], v[74:75], v[72:73]
	ds_read_b128 v[70:73], v78 offset:384
	s_waitcnt lgkmcnt(0)
	v_pk_fma_f32 v[40:41], v[68:69], v[72:73], v[40:41] op_sel_hi:[0,1,1] neg_lo:[1,0,0] neg_hi:[1,0,0]
	ds_read_b128 v[72:75], v78 offset:448
	v_pk_fma_f32 v[38:39], v[68:69], v[70:71], v[38:39] op_sel_hi:[0,1,1] neg_lo:[1,0,0] neg_hi:[1,0,0]
	s_waitcnt lgkmcnt(0)
	v_pk_fma_f32 v[72:73], v[68:69], v[72:73], v[34:35] op_sel_hi:[0,1,1] neg_lo:[1,0,0] neg_hi:[1,0,0]
	v_pk_fma_f32 v[70:71], v[68:69], v[74:75], v[36:37] op_sel_hi:[0,1,1] neg_lo:[1,0,0] neg_hi:[1,0,0]
	v_mul_f32_e32 v36, v72, v72
	v_pk_add_f32 v[34:35], v[76:77], v[76:77] op_sel:[0,1] op_sel_hi:[1,0]
	v_mul_f32_e32 v67, v73, v73
	v_mov_b32_e32 v35, v36
	v_pk_add_f32 v[36:37], v[80:81], v[80:81] op_sel:[0,1] op_sel_hi:[1,0]
	v_mul_f32_e32 v74, v41, v41
	v_mov_b32_e32 v37, v67
	v_pk_add_f32 v[34:35], v[34:35], v[36:37]
	v_mul_f32_e32 v36, v39, v39
	v_mul_f32_e32 v69, v70, v70
	v_mul_f32_e32 v79, v71, v71
	v_pk_fma_f32 v[36:37], v[38:39], v[38:39], v[36:37] op_sel_hi:[1,1,0]
	v_pk_fma_f32 v[74:75], v[40:41], v[40:41], v[74:75] op_sel_hi:[1,1,0]
	v_mov_b32_e32 v37, v69
	v_mov_b32_e32 v75, v79
	v_pk_add_f32 v[36:37], v[36:37], v[74:75]
	v_ashrrev_i32_e32 v67, 31, v66
	v_pk_add_f32 v[34:35], v[34:35], v[36:37]
	ds_read_b128 v[80:83], v78 offset:8448
	v_pk_add_f32 v[34:35], v[34:35], v[34:35] op_sel:[0,1] op_sel_hi:[1,0]
	v_lshlrev_b32_e32 v74, 3, v144
	v_mov_b32_e32 v35, v34
	s_nop 1
	v_permlane16_swap_b32_e32 v34, v35
	v_add_f32_e32 v69, v34, v35
	v_lshlrev_b64 v[34:35], 12, v[66:67]
	v_lshl_add_u64 v[34:35], s[12:13], 0, v[34:35]
	v_mov_b32_e32 v79, v69
	v_lshl_add_u64 v[34:35], v[34:35], 0, s[62:63]
	v_mov_b32_e32 v75, v0
	v_permlane32_swap_b32_e32 v69, v79
	v_lshl_add_u64 v[76:77], v[34:35], 0, v[74:75]
	global_load_dwordx4 v[208:211], v1, s[14:15]
	global_load_dwordx4 v[212:215], v1, s[14:15] offset:64
	global_load_dwordx4 v[216:219], v1, s[14:15] offset:128
	global_load_dwordx4 v[220:223], v1, s[14:15] offset:192
	global_load_dwordx4 v[224:227], v1, s[14:15] offset:256
	global_load_dwordx4 v[228:231], v1, s[14:15] offset:320
	global_load_dwordx4 v[244:247], v1, s[14:15] offset:384
	global_load_dwordx4 v[248:251], v1, s[14:15] offset:448
	s_waitcnt lgkmcnt(0)
	v_pk_fma_f32 v[32:33], v[68:69], v[82:83], v[32:33] op_sel_hi:[0,1,1] neg_lo:[1,0,0] neg_hi:[1,0,0]
	v_pk_fma_f32 v[30:31], v[68:69], v[80:81], v[30:31] op_sel_hi:[0,1,1] neg_lo:[1,0,0] neg_hi:[1,0,0]
	ds_read_b128 v[80:83], v78 offset:8512
	v_mov_b32_e32 v84, v33
	s_waitcnt lgkmcnt(0)
	v_pk_fma_f32 v[26:27], v[68:69], v[80:81], v[26:27] op_sel_hi:[0,1,1] neg_lo:[1,0,0] neg_hi:[1,0,0]
	v_pk_fma_f32 v[28:29], v[68:69], v[82:83], v[28:29] op_sel_hi:[0,1,1] neg_lo:[1,0,0] neg_hi:[1,0,0]
	v_mov_b32_e32 v82, v31
	v_mov_b32_e32 v83, v27
	v_mov_b32_e32 v80, v30
	v_mov_b32_e32 v81, v26
	v_pk_mul_f32 v[82:83], v[82:83], v[82:83]
	v_mov_b32_e32 v85, v29
	v_pk_fma_f32 v[80:81], v[80:81], v[80:81], v[82:83]
	v_mov_b32_e32 v82, v32
	v_mov_b32_e32 v83, v28
	v_pk_mul_f32 v[84:85], v[84:85], v[84:85]
	s_nop 0
	v_pk_fma_f32 v[82:83], v[82:83], v[82:83], v[84:85]
	s_nop 0
	v_pk_add_f32 v[84:85], v[80:81], v[82:83]
	ds_read_b128 v[80:83], v78 offset:8576
	s_waitcnt lgkmcnt(0)
	v_pk_fma_f32 v[22:23], v[68:69], v[80:81], v[22:23] op_sel_hi:[0,1,1] neg_lo:[1,0,0] neg_hi:[1,0,0]
	v_pk_fma_f32 v[24:25], v[68:69], v[82:83], v[24:25] op_sel_hi:[0,1,1] neg_lo:[1,0,0] neg_hi:[1,0,0]
	v_pk_mul_f32 v[80:81], v[24:25], v[24:25]
	v_pk_mul_f32 v[82:83], v[22:23], v[22:23]
	s_nop 0
	v_pk_mov_b32 v[86:87], v[82:83], v[80:81] op_sel:[1,0]
	v_mov_b32_e32 v83, v81
	v_pk_add_f32 v[86:87], v[86:87], v[82:83]
	ds_read_b128 v[80:83], v78 offset:8640
	s_waitcnt lgkmcnt(0)
	v_pk_fma_f32 v[20:21], v[68:69], v[82:83], v[20:21] op_sel_hi:[0,1,1] neg_lo:[1,0,0] neg_hi:[1,0,0]
	v_pk_fma_f32 v[18:19], v[68:69], v[80:81], v[18:19] op_sel_hi:[0,1,1] neg_lo:[1,0,0] neg_hi:[1,0,0]
	ds_read_b128 v[80:83], v78 offset:8704
	s_waitcnt lgkmcnt(0)
	v_pk_fma_f32 v[14:15], v[68:69], v[80:81], v[14:15] op_sel_hi:[0,1,1] neg_lo:[1,0,0] neg_hi:[1,0,0]
	v_pk_fma_f32 v[16:17], v[68:69], v[82:83], v[16:17] op_sel_hi:[0,1,1] neg_lo:[1,0,0] neg_hi:[1,0,0]
	v_mul_f32_e32 v67, v14, v14
	v_mul_f32_e32 v88, v15, v15
	v_pk_add_f32 v[80:81], v[84:85], v[84:85] op_sel:[0,1] op_sel_hi:[1,0]
	v_pk_add_f32 v[82:83], v[86:87], v[86:87] op_sel:[0,1] op_sel_hi:[1,0]
	v_mov_b32_e32 v81, v67
	v_mov_b32_e32 v83, v88
	v_pk_add_f32 v[80:81], v[80:81], v[82:83]
	v_mul_f32_e32 v82, v19, v19
	v_mul_f32_e32 v84, v21, v21
	v_mul_f32_e32 v89, v16, v16
	v_mul_f32_e32 v90, v17, v17
	v_pk_fma_f32 v[82:83], v[18:19], v[18:19], v[82:83] op_sel_hi:[1,1,0]
	v_pk_fma_f32 v[84:85], v[20:21], v[20:21], v[84:85] op_sel_hi:[1,1,0]
	v_mov_b32_e32 v83, v89
	v_mov_b32_e32 v85, v90
	v_pk_add_f32 v[82:83], v[82:83], v[84:85]
	s_nop 0
	v_pk_add_f32 v[84:85], v[80:81], v[82:83]
	ds_read_b128 v[80:83], v78 offset:8768
	s_waitcnt lgkmcnt(0)
	v_pk_fma_f32 v[10:11], v[68:69], v[80:81], v[10:11] op_sel_hi:[0,1,1] neg_lo:[1,0,0] neg_hi:[1,0,0]
	v_pk_fma_f32 v[12:13], v[68:69], v[82:83], v[12:13] op_sel_hi:[0,1,1] neg_lo:[1,0,0] neg_hi:[1,0,0]
	v_pk_mul_f32 v[80:81], v[12:13], v[12:13]
	v_pk_mul_f32 v[82:83], v[10:11], v[10:11]
	s_nop 0
	v_pk_mov_b32 v[86:87], v[82:83], v[80:81] op_sel:[1,0]
	v_mov_b32_e32 v83, v81
	v_pk_add_f32 v[86:87], v[86:87], v[82:83]
	ds_read_b128 v[80:83], v78 offset:8832
	s_waitcnt lgkmcnt(0)
	v_pk_fma_f32 v[8:9], v[68:69], v[82:83], v[8:9] op_sel_hi:[0,1,1] neg_lo:[1,0,0] neg_hi:[1,0,0]
	v_pk_fma_f32 v[6:7], v[68:69], v[80:81], v[6:7] op_sel_hi:[0,1,1] neg_lo:[1,0,0] neg_hi:[1,0,0]
	ds_read_b128 v[80:83], v78 offset:8896
	s_waitcnt lgkmcnt(0)
	v_pk_fma_f32 v[2:3], v[68:69], v[80:81], v[2:3] op_sel_hi:[0,1,1] neg_lo:[1,0,0] neg_hi:[1,0,0]
	v_pk_fma_f32 v[4:5], v[68:69], v[82:83], v[4:5] op_sel_hi:[0,1,1] neg_lo:[1,0,0] neg_hi:[1,0,0]
	v_mul_f32_e32 v67, v2, v2
	v_mul_f32_e32 v68, v3, v3
	v_pk_add_f32 v[80:81], v[84:85], v[84:85] op_sel:[0,1] op_sel_hi:[1,0]
	v_pk_add_f32 v[82:83], v[86:87], v[86:87] op_sel:[0,1] op_sel_hi:[1,0]
	v_mov_b32_e32 v81, v67
	v_mov_b32_e32 v83, v68
	v_mul_f32_e32 v68, v7, v7
	v_pk_add_f32 v[80:81], v[80:81], v[82:83]
	v_pk_fma_f32 v[82:83], v[6:7], v[6:7], v[68:69] op_sel_hi:[1,1,0]
	v_mul_f32_e32 v68, v9, v9
	v_mul_f32_e32 v78, v4, v4
	v_mul_f32_e32 v88, v5, v5
	v_pk_fma_f32 v[84:85], v[8:9], v[8:9], v[68:69] op_sel_hi:[1,1,0]
	v_mov_b32_e32 v83, v78
	v_mov_b32_e32 v85, v88
	v_pk_add_f32 v[82:83], v[82:83], v[84:85]
	s_nop 0
	v_pk_add_f32 v[80:81], v[80:81], v[82:83]
	s_nop 0
	v_pk_add_f32 v[80:81], v[80:81], v[80:81] op_sel:[0,1] op_sel_hi:[1,0]
	s_nop 0
	v_mov_b32_e32 v67, v80
	s_nop 1
	v_permlane16_swap_b32_e32 v80, v67
	v_add_f32_e32 v68, v80, v67
	v_mov_b32_e32 v78, v68
	s_nop 1
	v_permlane32_swap_b32_e32 v68, v78
	v_pk_add_f32 v[68:69], v[68:69], v[78:79]
	s_nop 0
	v_pk_fma_f32 v[68:69], v[68:69], s[4:5], v[178:179] op_sel_hi:[1,0,0]
	s_nop 0
	v_mul_f32_e32 v67, 0x4b800000, v69
	v_cmp_gt_f32_e64 s[4:5], s84, v69
	v_cmp_gt_f32_e32 vcc, s84, v68
	s_nop 0
	v_cndmask_b32_e64 v67, v69, v67, s[4:5]
	v_rsq_f32_e32 v67, v67
	s_nop 0
	v_mul_f32_e32 v69, 0x45800000, v67
	v_cndmask_b32_e64 v67, v67, v69, s[4:5]
	v_mul_f32_e32 v78, v147, v67
	v_pk_mul_f32 v[62:63], v[62:63], v[78:79] op_sel_hi:[1,0]
	v_pk_mul_f32 v[64:65], v[64:65], v[78:79] op_sel_hi:[1,0]
	s_waitcnt vmcnt(0)
	v_pk_mul_f32 v[34:35], v[208:209], v[62:63]
	v_pk_mul_f32 v[36:37], v[210:211], v[64:65]
	v_cvt_pk_bf16_f32 v34, v34, v35
	v_cvt_pk_bf16_f32 v35, v36, v37
	global_store_dwordx2 v[76:77], v[34:35], off offset:2048
	v_pk_mul_f32 v[58:59], v[58:59], v[78:79] op_sel_hi:[1,0]
	v_pk_mul_f32 v[60:61], v[60:61], v[78:79] op_sel_hi:[1,0]
	v_pk_mul_f32 v[54:55], v[54:55], v[78:79] op_sel_hi:[1,0]
	v_pk_mul_f32 v[56:57], v[56:57], v[78:79] op_sel_hi:[1,0]
	v_pk_mul_f32 v[50:51], v[50:51], v[78:79] op_sel_hi:[1,0]
	v_pk_mul_f32 v[52:53], v[52:53], v[78:79] op_sel_hi:[1,0]
	v_pk_mul_f32 v[46:47], v[46:47], v[78:79] op_sel_hi:[1,0]
	v_pk_mul_f32 v[48:49], v[48:49], v[78:79] op_sel_hi:[1,0]
	v_pk_mul_f32 v[42:43], v[42:43], v[78:79] op_sel_hi:[1,0]
	v_pk_mul_f32 v[44:45], v[44:45], v[78:79] op_sel_hi:[1,0]
	v_pk_mul_f32 v[38:39], v[38:39], v[78:79] op_sel_hi:[1,0]
	v_pk_mul_f32 v[40:41], v[40:41], v[78:79] op_sel_hi:[1,0]
	v_pk_mul_f32 v[36:37], v[214:215], v[60:61]
	v_pk_mul_f32 v[34:35], v[212:213], v[58:59]
	s_nop 0
	v_cvt_pk_bf16_f32 v34, v34, v35
	v_cvt_pk_bf16_f32 v35, v36, v37
	global_store_dwordx2 v[76:77], v[34:35], off offset:2080
	v_pk_mul_f32 v[36:37], v[218:219], v[56:57]
	v_pk_mul_f32 v[34:35], v[216:217], v[54:55]
	s_nop 0
	v_cvt_pk_bf16_f32 v34, v34, v35
	v_cvt_pk_bf16_f32 v35, v36, v37
	global_store_dwordx2 v[76:77], v[34:35], off offset:2112
	v_pk_mul_f32 v[36:37], v[222:223], v[52:53]
	v_pk_mul_f32 v[34:35], v[220:221], v[50:51]
	s_nop 0
	v_cvt_pk_bf16_f32 v34, v34, v35
	v_cvt_pk_bf16_f32 v35, v36, v37
	global_store_dwordx2 v[76:77], v[34:35], off offset:2144
	v_pk_mul_f32 v[36:37], v[226:227], v[48:49]
	v_pk_mul_f32 v[34:35], v[224:225], v[46:47]
	s_nop 0
	v_cvt_pk_bf16_f32 v34, v34, v35
	v_cvt_pk_bf16_f32 v35, v36, v37
	global_store_dwordx2 v[76:77], v[34:35], off offset:2176
	v_pk_mul_f32 v[36:37], v[230:231], v[44:45]
	v_pk_mul_f32 v[34:35], v[228:229], v[42:43]
	s_nop 0
	v_cvt_pk_bf16_f32 v34, v34, v35
	v_cvt_pk_bf16_f32 v35, v36, v37
	global_store_dwordx2 v[76:77], v[34:35], off offset:2208
	v_pk_mul_f32 v[36:37], v[246:247], v[40:41]
	v_pk_mul_f32 v[34:35], v[244:245], v[38:39]
	v_pk_mul_f32 v[38:39], v[72:73], v[78:79] op_sel_hi:[1,0]
	v_cvt_pk_bf16_f32 v34, v34, v35
	v_cvt_pk_bf16_f32 v35, v36, v37
	global_store_dwordx2 v[76:77], v[34:35], off offset:2240
	v_pk_mul_f32 v[40:41], v[70:71], v[78:79] op_sel_hi:[1,0]
	v_pk_mul_f32 v[34:35], v[38:39], v[248:249]
	v_pk_mul_f32 v[36:37], v[40:41], v[250:251]
	v_cvt_pk_bf16_f32 v34, v34, v35
	v_cvt_pk_bf16_f32 v35, v36, v37
	global_store_dwordx2 v[76:77], v[34:35], off offset:2272
	v_mul_f32_e32 v34, 0x4b800000, v68
	v_cndmask_b32_e32 v34, v68, v34, vcc
	v_rsq_f32_e32 v34, v34
	s_nop 0
	v_mul_f32_e32 v35, 0x45800000, v34
	v_cndmask_b32_e32 v34, v34, v35, vcc
	v_mul_f32_e32 v38, v147, v34
	v_or_b32_e32 v34, 16, v66
	v_ashrrev_i32_e32 v35, 31, v34
	v_lshlrev_b64 v[34:35], 12, v[34:35]
	v_lshl_add_u64 v[34:35], s[12:13], 0, v[34:35]
	v_lshl_add_u64 v[34:35], v[34:35], 0, s[62:63]
	v_lshl_add_u64 v[40:41], v[34:35], 0, v[74:75]
	v_pk_mul_f32 v[30:31], v[30:31], v[38:39] op_sel_hi:[1,0]
	v_pk_mul_f32 v[32:33], v[32:33], v[38:39] op_sel_hi:[1,0]
	v_pk_mul_f32 v[26:27], v[26:27], v[38:39] op_sel_hi:[1,0]
	v_pk_mul_f32 v[28:29], v[28:29], v[38:39] op_sel_hi:[1,0]
	v_pk_mul_f32 v[22:23], v[22:23], v[38:39] op_sel_hi:[1,0]
	v_pk_mul_f32 v[24:25], v[24:25], v[38:39] op_sel_hi:[1,0]
	v_pk_mul_f32 v[18:19], v[18:19], v[38:39] op_sel_hi:[1,0]
	v_pk_mul_f32 v[20:21], v[20:21], v[38:39] op_sel_hi:[1,0]
	v_pk_mul_f32 v[14:15], v[14:15], v[38:39] op_sel_hi:[1,0]
	v_pk_mul_f32 v[16:17], v[16:17], v[38:39] op_sel_hi:[1,0]
	v_pk_mul_f32 v[10:11], v[10:11], v[38:39] op_sel_hi:[1,0]
	v_pk_mul_f32 v[12:13], v[12:13], v[38:39] op_sel_hi:[1,0]
	v_pk_mul_f32 v[6:7], v[6:7], v[38:39] op_sel_hi:[1,0]
	v_pk_mul_f32 v[8:9], v[8:9], v[38:39] op_sel_hi:[1,0]
	v_pk_mul_f32 v[2:3], v[2:3], v[38:39] op_sel_hi:[1,0]
	v_pk_mul_f32 v[4:5], v[4:5], v[38:39] op_sel_hi:[1,0]
	v_pk_mul_f32 v[32:33], v[210:211], v[32:33]
	v_pk_mul_f32 v[30:31], v[208:209], v[30:31]
	s_nop 0
	v_cvt_pk_bf16_f32 v30, v30, v31
	v_cvt_pk_bf16_f32 v31, v32, v33
	global_store_dwordx2 v[40:41], v[30:31], off offset:2048
	v_pk_mul_f32 v[28:29], v[214:215], v[28:29]
	v_pk_mul_f32 v[26:27], v[212:213], v[26:27]
	s_nop 0
	v_cvt_pk_bf16_f32 v26, v26, v27
	v_cvt_pk_bf16_f32 v27, v28, v29
	global_store_dwordx2 v[40:41], v[26:27], off offset:2080
	v_pk_mul_f32 v[24:25], v[218:219], v[24:25]
	v_pk_mul_f32 v[22:23], v[216:217], v[22:23]
	s_nop 0
	v_cvt_pk_bf16_f32 v22, v22, v23
	v_cvt_pk_bf16_f32 v23, v24, v25
	global_store_dwordx2 v[40:41], v[22:23], off offset:2112
	v_pk_mul_f32 v[20:21], v[222:223], v[20:21]
	v_pk_mul_f32 v[18:19], v[220:221], v[18:19]
	s_nop 0
	v_cvt_pk_bf16_f32 v18, v18, v19
	v_cvt_pk_bf16_f32 v19, v20, v21
	global_store_dwordx2 v[40:41], v[18:19], off offset:2144
	v_pk_mul_f32 v[16:17], v[226:227], v[16:17]
	v_pk_mul_f32 v[14:15], v[224:225], v[14:15]
	s_nop 0
	v_cvt_pk_bf16_f32 v14, v14, v15
	v_cvt_pk_bf16_f32 v15, v16, v17
	global_store_dwordx2 v[40:41], v[14:15], off offset:2176
	v_pk_mul_f32 v[12:13], v[230:231], v[12:13]
	v_pk_mul_f32 v[10:11], v[228:229], v[10:11]
	s_nop 0
	v_cvt_pk_bf16_f32 v10, v10, v11
	v_cvt_pk_bf16_f32 v11, v12, v13
	global_store_dwordx2 v[40:41], v[10:11], off offset:2208
	v_pk_mul_f32 v[8:9], v[246:247], v[8:9]
	v_pk_mul_f32 v[6:7], v[244:245], v[6:7]
	s_nop 0
	v_cvt_pk_bf16_f32 v6, v6, v7
	v_cvt_pk_bf16_f32 v7, v8, v9
	global_store_dwordx2 v[40:41], v[6:7], off offset:2240
	v_pk_mul_f32 v[4:5], v[4:5], v[250:251]
	v_pk_mul_f32 v[2:3], v[2:3], v[248:249]
	s_nop 0
	v_cvt_pk_bf16_f32 v2, v2, v3
	v_cvt_pk_bf16_f32 v3, v4, v5
	global_store_dwordx2 v[40:41], v[2:3], off offset:2272
	s_branch .LBB0_1112
